# v18 + grid barrier: all blocks poll the top-level arrival counter against (gen+1)*nxcd instead of a separate generation word (one fabric hop less)
# baseline (speedup 1.0000x reference)
.LBB0_1900:
	s_or_b64 exec, exec, s[20:21]
	v_cvt_f32_u32_e32 v4, v2
	s_waitcnt vmcnt(1)
	v_readfirstlane_b32 s20, v3
	v_sub_u32_e32 v3, 0, v2
	v_rcp_iflag_f32_e32 v4, v4
	v_add_u32_e32 v5, s20, v1
	v_mul_f32_e32 v4, 0x4f7ffffe, v4
	v_cvt_u32_f32_e32 v4, v4
	v_mul_lo_u32 v1, v3, v4
	v_mul_hi_u32 v1, v4, v1
	v_add_u32_e32 v1, v4, v1
	v_mul_hi_u32 v1, v5, v1
	v_mul_lo_u32 v3, v1, v2
	v_sub_u32_e32 v3, v5, v3
	v_add_u32_e32 v4, 1, v1
	v_cmp_ge_u32_e32 vcc, v3, v2
	s_nop 1
	v_cndmask_b32_e32 v1, v1, v4, vcc
	v_sub_u32_e32 v4, v3, v2
	v_cndmask_b32_e32 v3, v3, v4, vcc
	v_add_u32_e32 v4, 1, v1
	v_cmp_ge_u32_e32 vcc, v3, v2
	v_add_u32_e32 v3, 1, v5
	s_nop 0
	v_cndmask_b32_e32 v1, v1, v4, vcc
	v_mul_lo_u32 v4, v2, v1
	v_add_u32_e32 v2, v4, v2
	v_cmp_ne_u32_e32 vcc, v3, v2
	s_and_saveexec_b64 s[20:21], vcc
	s_xor_b64 s[20:21], exec, s[20:21]
	s_cbranch_execz .LBB0_1914
	v_readlane_b32 s24, v233, 38
	v_readlane_b32 s25, v233, 39
	s_waitcnt lgkmcnt(0)
	s_nop 3
	v_mad_u32_u24 v6, v1, v0, v0
	global_load_dword v0, v33, s[24:25] sc1
	s_waitcnt vmcnt(0)
	v_cmp_gt_u32_e32 vcc, v6, v0
	s_and_saveexec_b64 s[28:29], vcc
	s_cbranch_execz .LBB0_1913
	s_mov_b32 s24, 1
	s_mov_b64 s[36:37], 0
	s_branch .LBB0_1904

.LBB0_1906:
	v_readlane_b32 s30, v233, 38
	v_readlane_b32 s31, v233, 39
	s_add_i32 s24, s24, 1
	s_mov_b64 s[42:43], -1
	s_nop 2
	global_load_dword v0, v33, s[30:31] sc1
	s_waitcnt vmcnt(0)
	v_cmp_le_u32_e32 vcc, v6, v0
	s_orn2_b64 s[40:41], vcc, exec
	s_branch .LBB0_1903

.LBB0_1917:
	s_or_b64 exec, exec, s[28:29]
	s_waitcnt vmcnt(0)
	v_readfirstlane_b32 s20, v2
	v_cvt_f32_u32_e32 v2, v0
	v_sub_u32_e32 v3, 0, v0
	v_add_u32_e32 v1, s20, v1
	v_readlane_b32 s20, v233, 40
	v_rcp_iflag_f32_e32 v2, v2
	v_readlane_b32 s21, v233, 41
	s_mov_b64 s[28:29], -1
	v_mul_f32_e32 v2, 0x4f7ffffe, v2
	v_cvt_u32_f32_e32 v2, v2
	v_mul_lo_u32 v3, v3, v2
	v_mul_hi_u32 v3, v2, v3
	v_add_u32_e32 v2, v2, v3
	v_mul_hi_u32 v2, v1, v2
	v_mul_lo_u32 v3, v2, v0
	v_sub_u32_e32 v3, v1, v3
	v_cmp_ge_u32_e32 vcc, v3, v0
	v_add_u32_e32 v4, 1, v2
	v_add_u32_e32 v1, 1, v1
	v_cndmask_b32_e32 v2, v2, v4, vcc
	v_sub_u32_e32 v4, v3, v0
	v_cndmask_b32_e32 v3, v3, v4, vcc
	v_cmp_ge_u32_e32 vcc, v3, v0
	v_add_u32_e32 v3, 1, v2
	s_nop 0
	v_cndmask_b32_e32 v2, v2, v3, vcc
	v_mul_lo_u32 v3, v0, v2
	v_add_u32_e32 v0, v3, v0
	v_cmp_ne_u32_e32 vcc, v1, v0
	v_mov_b32_e32 v6, v0
	v_mov_b64_e32 v[0:1], s[20:21]
	s_and_saveexec_b64 s[20:21], vcc
	s_cbranch_execz .LBB0_1929
	v_readlane_b32 s24, v233, 38
	v_readlane_b32 s25, v233, 39
	s_mov_b64 s[36:37], 0
	s_nop 3
	global_load_dword v0, v33, s[24:25] sc1
	s_waitcnt vmcnt(0)
	v_cmp_gt_u32_e32 vcc, v6, v0
	s_and_saveexec_b64 s[28:29], vcc
	s_cbranch_execz .LBB0_1928
	s_mov_b32 s24, 1
	s_branch .LBB0_1921
